# v112 + per-step RMSNorm: 8 rows per wave unrolled over a ring of four register sets (loads three rows ahead, stores left in flight)
# baseline (speedup 1.0000x reference)
; __global__ __launch_bounds__(512, 2) void mega(Params p, int s0, int s1) {
;     ...
;     for (int s = s0; s < s1; ++s) { run_step(p, s, lds);
;         if (s + 1 < s1) { if (s1 < 0) grid.sync(); else xcd_barrier(xb); } }
.Lfar_to_10:
	s_branch .LBB0_10
.Lfar_to_7:
	s_branch .LBB0_7
.Lfar_to_8:
	s_branch .LBB0_8
.Lfar_to_9:
	s_branch .LBB0_9

; __device__ __forceinline__ unsigned cvtpk(float lo, float hi) { unsigned r; asm volatile("v_cvt_pk_bf16_f32 %0, %1, %2" : "=v"(r) : "v"(lo), "v"(hi)); return r; }
; __device__ __forceinline__ int opq(int x) { asm volatile("" : "+v"(x)); return x; }
; __device__ __forceinline__ float wave_sum(float v) { for (int o = 32; o >= 1; o >>= 1) v += __shfl_xor(v, o); return v; }
; __device__ __forceinline__ void step_norm(const Params& p, int l, int g) {
;     const float* src = (l == 0) ? p.x : p.out; const float* gw = p.norm_g + l * DM;
;     const int tidq = opq(threadIdx.x), wid = tidq >> 6, lane = tidq & 63, gwv = blockIdx.x * 8 + wid, nwv = gridDim.x * 8;
;     for (int r = gwv; r < MG; r += nwv) {
;         const float* xr = src + (size_t)(g * MG + r) * DM; f32x4 v[4]; float ss = 0.f;
; #pragma unroll
;         for (int i = 0; i < 4; ++i) { v[i] = *(const f32x4*)(xr + lane * 4 + 256 * i); ss += v[i][0] * v[i][0] + v[i][1] * v[i][1] + v[i][2] * v[i][2] + v[i][3] * v[i][3]; }
;         ss = wave_sum(ss); const float rstd = rsqrtf(ss * (1.f / DM) + EPS);
; #pragma unroll
;         for (int i = 0; i < 4; ++i) { const f32x4 gv = *(const f32x4*)(gw + lane * 4 + 256 * i);
;             u32x2 o = {cvtpk(v[i][0] * rstd * gv[0], v[i][1] * rstd * gv[1]), cvtpk(v[i][2] * rstd * gv[2], v[i][3] * rstd * gv[3])};
;             *(u32x2*)(p.hbuf + (size_t)r * DM + lane * 4 + 256 * i) = o; }
.LBB0_1189:
	v_mov_b32_e32 v3, v198
	v_readlane_b32 s0, v251, 40
	v_ashrrev_i32_e32 v0, 6, v3
	s_nop 0
	v_add_u32_e32 v2, s0, v0
	s_movk_i32 s0, 0x4000
	v_cmp_gt_i32_e32 vcc, s0, v2
	s_and_saveexec_b64 s[0:1], vcc
	s_cbranch_execz .LBB0_1192
	v_and_b32_e32 v0, 64, v206
	v_add_u32_e32 v0, 64, v0
	v_xor_b32_e32 v4, 32, v206
	v_cmp_lt_i32_e32 vcc, v4, v0
	v_readlane_b32 s22, v251, 11
	v_readlane_b32 s23, v251, 12
	v_cndmask_b32_e32 v4, v206, v4, vcc
	v_lshlrev_b32_e32 v10, 2, v4
	v_xor_b32_e32 v4, 16, v206
	s_load_dword s20, s[22:23], 0x10
	s_nop 0
	s_load_dword s22, s[22:23], 0x0
	v_cmp_lt_i32_e32 vcc, v4, v0
	v_readlane_b32 s40, v253, 3
	v_readlane_b32 s44, v253, 7
	v_cndmask_b32_e32 v4, v206, v4, vcc
	v_lshlrev_b32_e32 v11, 2, v4
	v_xor_b32_e32 v4, 8, v206
	v_cmp_lt_i32_e32 vcc, v4, v0
	s_waitcnt lgkmcnt(0)
	s_lshr_b32 s20, s20, 16
	s_cmp_lg_u32 s20, 0
	v_cndmask_b32_e32 v4, v206, v4, vcc
	v_lshlrev_b32_e32 v12, 2, v4
	v_xor_b32_e32 v4, 4, v206
	s_cselect_b64 s[20:21], -1, 0
	v_cmp_lt_i32_e32 vcc, v4, v0
	s_cmp_lg_u64 s[20:21], 0
	s_addc_u32 s20, s22, 0
	v_cndmask_b32_e32 v4, v206, v4, vcc
	v_readlane_b32 s22, v251, 15
	v_readlane_b32 s45, v253, 8
	v_readlane_b32 s46, v253, 9
	v_readlane_b32 s47, v253, 10
	v_readlane_b32 s48, v253, 11
	v_readlane_b32 s49, v253, 12
	v_readlane_b32 s50, v253, 13
	v_readlane_b32 s51, v253, 14
	v_readlane_b32 s52, v253, 15
	v_readlane_b32 s53, v253, 16
	v_readlane_b32 s54, v253, 17
	v_readlane_b32 s55, v253, 18
	v_lshlrev_b32_e32 v13, 2, v4
	v_xor_b32_e32 v4, 2, v206
	s_add_i32 s21, s22, 9
	s_lshl_b32 s20, s20, 3
	v_readlane_b32 s44, v253, 22
	v_cmp_lt_i32_e32 vcc, v4, v0
	v_readlane_b32 s23, v251, 16
	s_cmp_lt_u32 s21, 19
	v_readlane_b32 s41, v253, 4
	v_readlane_b32 s58, v253, 36
	v_readlane_b32 s59, v253, 37
	v_readlane_b32 s24, v253, 49
	v_cndmask_b32_e32 v4, v206, v4, vcc
	s_cselect_b32 s23, s41, s59
	s_cselect_b32 s22, s40, s58
	v_readlane_b32 s25, v253, 50
	s_lshl_b32 s24, s24, 10
	v_lshlrev_b32_e32 v14, 2, v4
	v_xor_b32_e32 v4, 1, v206
	s_ashr_i32 s25, s24, 31
	v_cmp_lt_i32_e32 vcc, v4, v0
	v_readlane_b32 s42, v253, 5
	s_lshl_b64 s[24:25], s[24:25], 2
	v_cndmask_b32_e32 v0, v206, v4, vcc
	v_readlane_b32 s21, v253, 51
	v_readlane_b32 s43, v253, 6
	s_add_u32 s24, s42, s24
	v_lshlrev_b32_e32 v15, 2, v0
	v_lshlrev_b32_e32 v0, 4, v3
	v_lshl_add_u32 v6, s21, 14, v2
	s_addc_u32 s25, s43, s25
	v_and_b32_e32 v0, 0x3f0, v0
	v_ashrrev_i32_e32 v7, 31, v6
	v_lshl_add_u64 v[4:5], s[24:25], 0, v[0:1]
	v_lshlrev_b64 v[6:7], 12, v[6:7]
	v_and_b32_e32 v0, 63, v3
	v_ashrrev_i32_e32 v3, 31, v2
	v_lshl_or_b32 v6, v0, 4, v6
	v_lshlrev_b64 v[8:9], 11, v[2:3]
	v_readlane_b32 s24, v253, 20
	v_lshl_add_u64 v[6:7], s[22:23], 0, v[6:7]
	s_ashr_i32 s21, s20, 31
	v_lshl_or_b32 v8, v0, 3, v8
	v_readlane_b32 s25, v253, 21
	v_lshl_add_u64 v[6:7], v[6:7], 0, s[90:91]
	s_lshl_b64 s[22:23], s[20:21], 12
	v_lshl_add_u64 v[8:9], s[24:25], 0, v[8:9]
	s_lshl_b64 s[24:25], s[20:21], 11
	s_mov_b64 s[26:27], 0
	v_readlane_b32 s45, v253, 23
	v_readlane_b32 s46, v253, 24
	v_readlane_b32 s47, v253, 25
	v_readlane_b32 s48, v253, 26
	v_readlane_b32 s49, v253, 27
	v_readlane_b32 s50, v253, 28
	v_readlane_b32 s51, v253, 29
	v_readlane_b32 s52, v253, 30
	v_readlane_b32 s53, v253, 31
	v_readlane_b32 s54, v253, 32
	v_readlane_b32 s55, v253, 33
	v_readlane_b32 s56, v253, 34
	v_readlane_b32 s57, v253, 35
	global_load_dwordx4 v[32:35], v[4:5], off
	global_load_dwordx4 v[52:55], v[4:5], off offset:1024
	global_load_dwordx4 v[56:59], v[4:5], off offset:2048
	global_load_dwordx4 v[60:63], v[4:5], off offset:3072
	global_load_dwordx4 v[16:19], v[6:7], off offset:-2048
	global_load_dwordx4 v[20:23], v[6:7], off offset:-1024
	global_load_dwordx4 v[24:27], v[6:7], off
	global_load_dwordx4 v[28:31], v[6:7], off offset:1024
	v_lshl_add_u64 v[6:7], v[6:7], 0, s[22:23]
	global_load_dwordx4 v[64:67], v[6:7], off offset:-2048
	global_load_dwordx4 v[68:71], v[6:7], off offset:-1024
	global_load_dwordx4 v[72:75], v[6:7], off
	global_load_dwordx4 v[76:79], v[6:7], off offset:1024
	v_lshl_add_u64 v[6:7], v[6:7], 0, s[22:23]
	global_load_dwordx4 v[80:83], v[6:7], off offset:-2048
	global_load_dwordx4 v[84:87], v[6:7], off offset:-1024
	global_load_dwordx4 v[88:91], v[6:7], off
	global_load_dwordx4 v[92:95], v[6:7], off offset:1024
	v_lshl_add_u64 v[6:7], v[6:7], 0, s[22:23]
	global_load_dwordx4 v[96:99], v[6:7], off offset:-2048
	global_load_dwordx4 v[100:103], v[6:7], off offset:-1024
	global_load_dwordx4 v[104:107], v[6:7], off
	global_load_dwordx4 v[108:111], v[6:7], off offset:1024
	s_waitcnt vmcnt(12)
	v_mov_b32_e32 v38, v17
	v_mov_b32_e32 v39, v21
	v_mov_b32_e32 v36, v16
	v_mov_b32_e32 v37, v20
	v_mov_b32_e32 v46, v25
	v_mov_b32_e32 v47, v29
	v_pk_mul_f32 v[38:39], v[38:39], v[38:39]
	v_mov_b32_e32 v40, v18
	v_mov_b32_e32 v41, v22
	v_mov_b32_e32 v44, v24
	v_mov_b32_e32 v45, v28
	v_pk_mul_f32 v[46:47], v[46:47], v[46:47]
	v_pk_fma_f32 v[36:37], v[36:37], v[36:37], v[38:39]
	v_mov_b32_e32 v42, v19
	v_mov_b32_e32 v43, v23
	v_mov_b32_e32 v48, v26
	v_mov_b32_e32 v49, v30
	v_pk_fma_f32 v[38:39], v[44:45], v[44:45], v[46:47]
	v_pk_fma_f32 v[36:37], v[40:41], v[40:41], v[36:37]
	v_mov_b32_e32 v50, v27
	v_mov_b32_e32 v51, v31
	v_pk_fma_f32 v[38:39], v[48:49], v[48:49], v[38:39]
	v_pk_fma_f32 v[36:37], v[42:43], v[42:43], v[36:37]
	v_pk_fma_f32 v[38:39], v[50:51], v[50:51], v[38:39]
	v_add_f32_e32 v0, v36, v37
	v_add_f32_e32 v0, v0, v38
	v_add_f32_e32 v0, v0, v39
	ds_bpermute_b32 v3, v10, v0
	s_waitcnt lgkmcnt(0)
	v_add_f32_e32 v0, v0, v3
	ds_bpermute_b32 v3, v11, v0
	s_waitcnt lgkmcnt(0)
	v_add_f32_e32 v0, v0, v3
	ds_bpermute_b32 v3, v12, v0
	s_waitcnt lgkmcnt(0)
; __device__ __forceinline__ unsigned cvtpk(float lo, float hi) { unsigned r; asm volatile("v_cvt_pk_bf16_f32 %0, %1, %2" : "=v"(r) : "v"(lo), "v"(hi)); return r; }
; __device__ __forceinline__ float wave_sum(float v) { for (int o = 32; o >= 1; o >>= 1) v += __shfl_xor(v, o); return v; }
; __device__ __forceinline__ void step_norm(const Params& p, int l, int g) {
;     ...
;     for (int r = gwv; r < MG; r += nwv) {
;         const float* xr = src + (size_t)(g * MG + r) * DM; f32x4 v[4]; float ss = 0.f;
; #pragma unroll
;         for (int i = 0; i < 4; ++i) { v[i] = *(const f32x4*)(xr + lane * 4 + 256 * i); ss += v[i][0] * v[i][0] + v[i][1] * v[i][1] + v[i][2] * v[i][2] + v[i][3] * v[i][3]; }
;         ss = wave_sum(ss); const float rstd = rsqrtf(ss * (1.f / DM) + EPS);
; #pragma unroll
;         for (int i = 0; i < 4; ++i) { const f32x4 gv = *(const f32x4*)(gw + lane * 4 + 256 * i);
;             u32x2 o = {cvtpk(v[i][0] * rstd * gv[0], v[i][1] * rstd * gv[1]), cvtpk(v[i][2] * rstd * gv[2], v[i][3] * rstd * gv[3])};
;             *(u32x2*)(p.hbuf + (size_t)r * DM + lane * 4 + 256 * i) = o; }
	v_add_f32_e32 v0, v0, v3
	ds_bpermute_b32 v3, v13, v0
	s_waitcnt lgkmcnt(0)
	v_add_f32_e32 v0, v0, v3
	ds_bpermute_b32 v3, v14, v0
	s_waitcnt lgkmcnt(0)
	v_add_f32_e32 v0, v0, v3
	ds_bpermute_b32 v3, v15, v0
	s_waitcnt lgkmcnt(0)
	v_add_f32_e32 v0, v0, v3
	v_fmamk_f32 v0, v0, 0x3a800000, v199
	v_mul_f32_e32 v3, 0x4b800000, v0
	v_cmp_gt_f32_e32 vcc, s85, v0
	s_nop 1
	v_cndmask_b32_e32 v0, v0, v3, vcc
	v_rsq_f32_e32 v0, v0
	s_nop 0
	v_mul_f32_e32 v3, 0x45800000, v0
	v_cndmask_b32_e32 v0, v0, v3, vcc
	v_mul_f32_e32 v40, v16, v0
	v_mul_f32_e32 v41, v17, v0
	v_mul_f32_e32 v42, v18, v0
	v_mul_f32_e32 v43, v19, v0
	v_mul_f32_e32 v40, v32, v40
	v_mul_f32_e32 v41, v33, v41
	v_mul_f32_e32 v42, v34, v42
	v_mul_f32_e32 v43, v35, v43
	v_cvt_pk_bf16_f32 v48, v40, v41
	v_cvt_pk_bf16_f32 v49, v42, v43
	global_store_dwordx2 v[8:9], v[48:49], off offset:-1024
	v_mul_f32_e32 v44, v20, v0
	v_mul_f32_e32 v45, v21, v0
	v_mul_f32_e32 v46, v22, v0
	v_mul_f32_e32 v47, v23, v0
	v_mul_f32_e32 v44, v52, v44
	v_mul_f32_e32 v45, v53, v45
	v_mul_f32_e32 v46, v54, v46
	v_mul_f32_e32 v47, v55, v47
	v_cvt_pk_bf16_f32 v50, v44, v45
	v_cvt_pk_bf16_f32 v51, v46, v47
	global_store_dwordx2 v[8:9], v[50:51], off offset:-512
	v_mul_f32_e32 v40, v24, v0
	v_mul_f32_e32 v41, v25, v0
	v_mul_f32_e32 v42, v26, v0
	v_mul_f32_e32 v43, v27, v0
	v_mul_f32_e32 v40, v56, v40
	v_mul_f32_e32 v41, v57, v41
	v_mul_f32_e32 v42, v58, v42
	v_mul_f32_e32 v43, v59, v43
	v_cvt_pk_bf16_f32 v48, v40, v41
	v_cvt_pk_bf16_f32 v49, v42, v43
	global_store_dwordx2 v[8:9], v[48:49], off
	v_mul_f32_e32 v44, v28, v0
	v_mul_f32_e32 v45, v29, v0
	v_mul_f32_e32 v46, v30, v0
	v_mul_f32_e32 v47, v31, v0
	v_mul_f32_e32 v44, v60, v44
	v_mul_f32_e32 v45, v61, v45
	v_mul_f32_e32 v46, v62, v46
	v_mul_f32_e32 v47, v63, v47
	v_cvt_pk_bf16_f32 v50, v44, v45
	v_cvt_pk_bf16_f32 v51, v46, v47
	global_store_dwordx2 v[8:9], v[50:51], off offset:512
	v_lshl_add_u64 v[8:9], v[8:9], 0, s[24:25]
	v_lshl_add_u64 v[6:7], v[6:7], 0, s[22:23]
	global_load_dwordx4 v[16:19], v[6:7], off offset:-2048
	global_load_dwordx4 v[20:23], v[6:7], off offset:-1024
	global_load_dwordx4 v[24:27], v[6:7], off
	global_load_dwordx4 v[28:31], v[6:7], off offset:1024
	s_waitcnt vmcnt(16)
	v_mov_b32_e32 v38, v65
	v_mov_b32_e32 v39, v69
	v_mov_b32_e32 v36, v64
	v_mov_b32_e32 v37, v68
	v_mov_b32_e32 v46, v73
	v_mov_b32_e32 v47, v77
	v_pk_mul_f32 v[38:39], v[38:39], v[38:39]
	v_mov_b32_e32 v40, v66
	v_mov_b32_e32 v41, v70
	v_mov_b32_e32 v44, v72
	v_mov_b32_e32 v45, v76
	v_pk_mul_f32 v[46:47], v[46:47], v[46:47]
	v_pk_fma_f32 v[36:37], v[36:37], v[36:37], v[38:39]
	v_mov_b32_e32 v42, v67
	v_mov_b32_e32 v43, v71
	v_mov_b32_e32 v48, v74
	v_mov_b32_e32 v49, v78
	v_pk_fma_f32 v[38:39], v[44:45], v[44:45], v[46:47]
	v_pk_fma_f32 v[36:37], v[40:41], v[40:41], v[36:37]
	v_mov_b32_e32 v50, v75
	v_mov_b32_e32 v51, v79
	v_pk_fma_f32 v[38:39], v[48:49], v[48:49], v[38:39]
	v_pk_fma_f32 v[36:37], v[42:43], v[42:43], v[36:37]
	v_pk_fma_f32 v[38:39], v[50:51], v[50:51], v[38:39]
	v_add_f32_e32 v0, v36, v37
	v_add_f32_e32 v0, v0, v38
	v_add_f32_e32 v0, v0, v39
	ds_bpermute_b32 v3, v10, v0
	s_waitcnt lgkmcnt(0)
	v_add_f32_e32 v0, v0, v3
	ds_bpermute_b32 v3, v11, v0
	s_waitcnt lgkmcnt(0)
	v_add_f32_e32 v0, v0, v3
	ds_bpermute_b32 v3, v12, v0
	s_waitcnt lgkmcnt(0)
	v_add_f32_e32 v0, v0, v3
	ds_bpermute_b32 v3, v13, v0
	s_waitcnt lgkmcnt(0)
	v_add_f32_e32 v0, v0, v3
	ds_bpermute_b32 v3, v14, v0
	s_waitcnt lgkmcnt(0)
	v_add_f32_e32 v0, v0, v3
	ds_bpermute_b32 v3, v15, v0
	s_waitcnt lgkmcnt(0)
	v_add_f32_e32 v0, v0, v3
	v_fmamk_f32 v0, v0, 0x3a800000, v199
	v_mul_f32_e32 v3, 0x4b800000, v0
	v_cmp_gt_f32_e32 vcc, s85, v0
	s_nop 1
	v_cndmask_b32_e32 v0, v0, v3, vcc
	v_rsq_f32_e32 v0, v0
	s_nop 0
	v_mul_f32_e32 v3, 0x45800000, v0
	v_cndmask_b32_e32 v0, v0, v3, vcc
	v_mul_f32_e32 v40, v64, v0
	v_mul_f32_e32 v41, v65, v0
	v_mul_f32_e32 v42, v66, v0
	v_mul_f32_e32 v43, v67, v0
	v_mul_f32_e32 v40, v32, v40
	v_mul_f32_e32 v41, v33, v41
	v_mul_f32_e32 v42, v34, v42
	v_mul_f32_e32 v43, v35, v43
	v_cvt_pk_bf16_f32 v48, v40, v41
	v_cvt_pk_bf16_f32 v49, v42, v43
	global_store_dwordx2 v[8:9], v[48:49], off offset:-1024
	v_mul_f32_e32 v44, v68, v0
	v_mul_f32_e32 v45, v69, v0
	v_mul_f32_e32 v46, v70, v0
	v_mul_f32_e32 v47, v71, v0
	v_mul_f32_e32 v44, v52, v44
	v_mul_f32_e32 v45, v53, v45
	v_mul_f32_e32 v46, v54, v46
	v_mul_f32_e32 v47, v55, v47
	v_cvt_pk_bf16_f32 v50, v44, v45
	v_cvt_pk_bf16_f32 v51, v46, v47
	global_store_dwordx2 v[8:9], v[50:51], off offset:-512
	v_mul_f32_e32 v40, v72, v0
	v_mul_f32_e32 v41, v73, v0
	v_mul_f32_e32 v42, v74, v0
	v_mul_f32_e32 v43, v75, v0
	v_mul_f32_e32 v40, v56, v40
	v_mul_f32_e32 v41, v57, v41
	v_mul_f32_e32 v42, v58, v42
	v_mul_f32_e32 v43, v59, v43
	v_cvt_pk_bf16_f32 v48, v40, v41
	v_cvt_pk_bf16_f32 v49, v42, v43
	global_store_dwordx2 v[8:9], v[48:49], off
	v_mul_f32_e32 v44, v76, v0
	v_mul_f32_e32 v45, v77, v0
	v_mul_f32_e32 v46, v78, v0
	v_mul_f32_e32 v47, v79, v0
	v_mul_f32_e32 v44, v60, v44
	v_mul_f32_e32 v45, v61, v45
	v_mul_f32_e32 v46, v62, v46
	v_mul_f32_e32 v47, v63, v47
	v_cvt_pk_bf16_f32 v50, v44, v45
	v_cvt_pk_bf16_f32 v51, v46, v47
	global_store_dwordx2 v[8:9], v[50:51], off offset:512
	v_lshl_add_u64 v[8:9], v[8:9], 0, s[24:25]
	v_lshl_add_u64 v[6:7], v[6:7], 0, s[22:23]
	global_load_dwordx4 v[64:67], v[6:7], off offset:-2048
	global_load_dwordx4 v[68:71], v[6:7], off offset:-1024
	global_load_dwordx4 v[72:75], v[6:7], off
	global_load_dwordx4 v[76:79], v[6:7], off offset:1024
	s_waitcnt vmcnt(20)
; __device__ __forceinline__ unsigned cvtpk(float lo, float hi) { unsigned r; asm volatile("v_cvt_pk_bf16_f32 %0, %1, %2" : "=v"(r) : "v"(lo), "v"(hi)); return r; }
; __device__ __forceinline__ float wave_sum(float v) { for (int o = 32; o >= 1; o >>= 1) v += __shfl_xor(v, o); return v; }
; __device__ __forceinline__ void step_norm(const Params& p, int l, int g) {
;     ...
;     for (int r = gwv; r < MG; r += nwv) {
;         const float* xr = src + (size_t)(g * MG + r) * DM; f32x4 v[4]; float ss = 0.f;
; #pragma unroll
;         for (int i = 0; i < 4; ++i) { v[i] = *(const f32x4*)(xr + lane * 4 + 256 * i); ss += v[i][0] * v[i][0] + v[i][1] * v[i][1] + v[i][2] * v[i][2] + v[i][3] * v[i][3]; }
;         ss = wave_sum(ss); const float rstd = rsqrtf(ss * (1.f / DM) + EPS);
; #pragma unroll
;         for (int i = 0; i < 4; ++i) { const f32x4 gv = *(const f32x4*)(gw + lane * 4 + 256 * i);
;             u32x2 o = {cvtpk(v[i][0] * rstd * gv[0], v[i][1] * rstd * gv[1]), cvtpk(v[i][2] * rstd * gv[2], v[i][3] * rstd * gv[3])};
;             *(u32x2*)(p.hbuf + (size_t)r * DM + lane * 4 + 256 * i) = o; }
	v_mov_b32_e32 v38, v81
	v_mov_b32_e32 v39, v85
	v_mov_b32_e32 v36, v80
	v_mov_b32_e32 v37, v84
	v_mov_b32_e32 v46, v89
	v_mov_b32_e32 v47, v93
	v_pk_mul_f32 v[38:39], v[38:39], v[38:39]
	v_mov_b32_e32 v40, v82
	v_mov_b32_e32 v41, v86
	v_mov_b32_e32 v44, v88
	v_mov_b32_e32 v45, v92
	v_pk_mul_f32 v[46:47], v[46:47], v[46:47]
	v_pk_fma_f32 v[36:37], v[36:37], v[36:37], v[38:39]
	v_mov_b32_e32 v42, v83
	v_mov_b32_e32 v43, v87
	v_mov_b32_e32 v48, v90
	v_mov_b32_e32 v49, v94
	v_pk_fma_f32 v[38:39], v[44:45], v[44:45], v[46:47]
	v_pk_fma_f32 v[36:37], v[40:41], v[40:41], v[36:37]
	v_mov_b32_e32 v50, v91
	v_mov_b32_e32 v51, v95
	v_pk_fma_f32 v[38:39], v[48:49], v[48:49], v[38:39]
	v_pk_fma_f32 v[36:37], v[42:43], v[42:43], v[36:37]
	v_pk_fma_f32 v[38:39], v[50:51], v[50:51], v[38:39]
	v_add_f32_e32 v0, v36, v37
	v_add_f32_e32 v0, v0, v38
	v_add_f32_e32 v0, v0, v39
	ds_bpermute_b32 v3, v10, v0
	s_waitcnt lgkmcnt(0)
	v_add_f32_e32 v0, v0, v3
	ds_bpermute_b32 v3, v11, v0
	s_waitcnt lgkmcnt(0)
	v_add_f32_e32 v0, v0, v3
	ds_bpermute_b32 v3, v12, v0
	s_waitcnt lgkmcnt(0)
	v_add_f32_e32 v0, v0, v3
	ds_bpermute_b32 v3, v13, v0
	s_waitcnt lgkmcnt(0)
	v_add_f32_e32 v0, v0, v3
	ds_bpermute_b32 v3, v14, v0
	s_waitcnt lgkmcnt(0)
	v_add_f32_e32 v0, v0, v3
	ds_bpermute_b32 v3, v15, v0
	s_waitcnt lgkmcnt(0)
	v_add_f32_e32 v0, v0, v3
	v_fmamk_f32 v0, v0, 0x3a800000, v199
	v_mul_f32_e32 v3, 0x4b800000, v0
	v_cmp_gt_f32_e32 vcc, s85, v0
	s_nop 1
	v_cndmask_b32_e32 v0, v0, v3, vcc
	v_rsq_f32_e32 v0, v0
	s_nop 0
	v_mul_f32_e32 v3, 0x45800000, v0
	v_cndmask_b32_e32 v0, v0, v3, vcc
	v_mul_f32_e32 v40, v80, v0
	v_mul_f32_e32 v41, v81, v0
	v_mul_f32_e32 v42, v82, v0
	v_mul_f32_e32 v43, v83, v0
	v_mul_f32_e32 v40, v32, v40
	v_mul_f32_e32 v41, v33, v41
	v_mul_f32_e32 v42, v34, v42
	v_mul_f32_e32 v43, v35, v43
	v_cvt_pk_bf16_f32 v48, v40, v41
	v_cvt_pk_bf16_f32 v49, v42, v43
	global_store_dwordx2 v[8:9], v[48:49], off offset:-1024
	v_mul_f32_e32 v44, v84, v0
	v_mul_f32_e32 v45, v85, v0
	v_mul_f32_e32 v46, v86, v0
	v_mul_f32_e32 v47, v87, v0
	v_mul_f32_e32 v44, v52, v44
	v_mul_f32_e32 v45, v53, v45
	v_mul_f32_e32 v46, v54, v46
	v_mul_f32_e32 v47, v55, v47
	v_cvt_pk_bf16_f32 v50, v44, v45
	v_cvt_pk_bf16_f32 v51, v46, v47
	global_store_dwordx2 v[8:9], v[50:51], off offset:-512
	v_mul_f32_e32 v40, v88, v0
	v_mul_f32_e32 v41, v89, v0
	v_mul_f32_e32 v42, v90, v0
	v_mul_f32_e32 v43, v91, v0
	v_mul_f32_e32 v40, v56, v40
	v_mul_f32_e32 v41, v57, v41
	v_mul_f32_e32 v42, v58, v42
	v_mul_f32_e32 v43, v59, v43
	v_cvt_pk_bf16_f32 v48, v40, v41
	v_cvt_pk_bf16_f32 v49, v42, v43
	global_store_dwordx2 v[8:9], v[48:49], off
	v_mul_f32_e32 v44, v92, v0
	v_mul_f32_e32 v45, v93, v0
	v_mul_f32_e32 v46, v94, v0
	v_mul_f32_e32 v47, v95, v0
	v_mul_f32_e32 v44, v60, v44
	v_mul_f32_e32 v45, v61, v45
	v_mul_f32_e32 v46, v62, v46
	v_mul_f32_e32 v47, v63, v47
	v_cvt_pk_bf16_f32 v50, v44, v45
	v_cvt_pk_bf16_f32 v51, v46, v47
	global_store_dwordx2 v[8:9], v[50:51], off offset:512
	v_lshl_add_u64 v[8:9], v[8:9], 0, s[24:25]
	v_lshl_add_u64 v[6:7], v[6:7], 0, s[22:23]
	global_load_dwordx4 v[80:83], v[6:7], off offset:-2048
	global_load_dwordx4 v[84:87], v[6:7], off offset:-1024
	global_load_dwordx4 v[88:91], v[6:7], off
	global_load_dwordx4 v[92:95], v[6:7], off offset:1024
	s_waitcnt vmcnt(24)
	v_mov_b32_e32 v38, v97
	v_mov_b32_e32 v39, v101
	v_mov_b32_e32 v36, v96
	v_mov_b32_e32 v37, v100
	v_mov_b32_e32 v46, v105
	v_mov_b32_e32 v47, v109
	v_pk_mul_f32 v[38:39], v[38:39], v[38:39]
	v_mov_b32_e32 v40, v98
	v_mov_b32_e32 v41, v102
	v_mov_b32_e32 v44, v104
	v_mov_b32_e32 v45, v108
	v_pk_mul_f32 v[46:47], v[46:47], v[46:47]
	v_pk_fma_f32 v[36:37], v[36:37], v[36:37], v[38:39]
	v_mov_b32_e32 v42, v99
	v_mov_b32_e32 v43, v103
	v_mov_b32_e32 v48, v106
	v_mov_b32_e32 v49, v110
	v_pk_fma_f32 v[38:39], v[44:45], v[44:45], v[46:47]
	v_pk_fma_f32 v[36:37], v[40:41], v[40:41], v[36:37]
	v_mov_b32_e32 v50, v107
	v_mov_b32_e32 v51, v111
	v_pk_fma_f32 v[38:39], v[48:49], v[48:49], v[38:39]
	v_pk_fma_f32 v[36:37], v[42:43], v[42:43], v[36:37]
	v_pk_fma_f32 v[38:39], v[50:51], v[50:51], v[38:39]
	v_add_f32_e32 v0, v36, v37
	v_add_f32_e32 v0, v0, v38
	v_add_f32_e32 v0, v0, v39
	ds_bpermute_b32 v3, v10, v0
	s_waitcnt lgkmcnt(0)
	v_add_f32_e32 v0, v0, v3
	ds_bpermute_b32 v3, v11, v0
	s_waitcnt lgkmcnt(0)
	v_add_f32_e32 v0, v0, v3
	ds_bpermute_b32 v3, v12, v0
	s_waitcnt lgkmcnt(0)
	v_add_f32_e32 v0, v0, v3
	ds_bpermute_b32 v3, v13, v0
	s_waitcnt lgkmcnt(0)
	v_add_f32_e32 v0, v0, v3
	ds_bpermute_b32 v3, v14, v0
	s_waitcnt lgkmcnt(0)
	v_add_f32_e32 v0, v0, v3
	ds_bpermute_b32 v3, v15, v0
	s_waitcnt lgkmcnt(0)
	v_add_f32_e32 v0, v0, v3
	v_fmamk_f32 v0, v0, 0x3a800000, v199
	v_mul_f32_e32 v3, 0x4b800000, v0
	v_cmp_gt_f32_e32 vcc, s85, v0
	s_nop 1
	v_cndmask_b32_e32 v0, v0, v3, vcc
	v_rsq_f32_e32 v0, v0
	s_nop 0
	v_mul_f32_e32 v3, 0x45800000, v0
	v_cndmask_b32_e32 v0, v0, v3, vcc
	v_mul_f32_e32 v40, v96, v0
	v_mul_f32_e32 v41, v97, v0
	v_mul_f32_e32 v42, v98, v0
	v_mul_f32_e32 v43, v99, v0
	v_mul_f32_e32 v40, v32, v40
	v_mul_f32_e32 v41, v33, v41
	v_mul_f32_e32 v42, v34, v42
	v_mul_f32_e32 v43, v35, v43
	v_cvt_pk_bf16_f32 v48, v40, v41
	v_cvt_pk_bf16_f32 v49, v42, v43
	global_store_dwordx2 v[8:9], v[48:49], off offset:-1024
	v_mul_f32_e32 v44, v100, v0
	v_mul_f32_e32 v45, v101, v0
	v_mul_f32_e32 v46, v102, v0
	v_mul_f32_e32 v47, v103, v0
	v_mul_f32_e32 v44, v52, v44
	v_mul_f32_e32 v45, v53, v45
	v_mul_f32_e32 v46, v54, v46
	v_mul_f32_e32 v47, v55, v47
	v_cvt_pk_bf16_f32 v50, v44, v45
	v_cvt_pk_bf16_f32 v51, v46, v47
	global_store_dwordx2 v[8:9], v[50:51], off offset:-512
	v_mul_f32_e32 v40, v104, v0
	v_mul_f32_e32 v41, v105, v0
	v_mul_f32_e32 v42, v106, v0
	v_mul_f32_e32 v43, v107, v0
	v_mul_f32_e32 v40, v56, v40
	v_mul_f32_e32 v41, v57, v41
	v_mul_f32_e32 v42, v58, v42
	v_mul_f32_e32 v43, v59, v43
	v_cvt_pk_bf16_f32 v48, v40, v41
	v_cvt_pk_bf16_f32 v49, v42, v43
	global_store_dwordx2 v[8:9], v[48:49], off
	v_mul_f32_e32 v44, v108, v0
	v_mul_f32_e32 v45, v109, v0
	v_mul_f32_e32 v46, v110, v0
	v_mul_f32_e32 v47, v111, v0
	v_mul_f32_e32 v44, v60, v44
	v_mul_f32_e32 v45, v61, v45
	v_mul_f32_e32 v46, v62, v46
	v_mul_f32_e32 v47, v63, v47
	v_cvt_pk_bf16_f32 v50, v44, v45
	v_cvt_pk_bf16_f32 v51, v46, v47
	global_store_dwordx2 v[8:9], v[50:51], off offset:512
	v_lshl_add_u64 v[8:9], v[8:9], 0, s[24:25]
	v_lshl_add_u64 v[6:7], v[6:7], 0, s[22:23]
	global_load_dwordx4 v[96:99], v[6:7], off offset:-2048
	global_load_dwordx4 v[100:103], v[6:7], off offset:-1024
	global_load_dwordx4 v[104:107], v[6:7], off
	global_load_dwordx4 v[108:111], v[6:7], off offset:1024
	s_waitcnt vmcnt(24)
; __device__ __forceinline__ unsigned cvtpk(float lo, float hi) { unsigned r; asm volatile("v_cvt_pk_bf16_f32 %0, %1, %2" : "=v"(r) : "v"(lo), "v"(hi)); return r; }
; __device__ __forceinline__ float wave_sum(float v) { for (int o = 32; o >= 1; o >>= 1) v += __shfl_xor(v, o); return v; }
; __device__ __forceinline__ void step_norm(const Params& p, int l, int g) {
;     ...
;     for (int r = gwv; r < MG; r += nwv) {
;         const float* xr = src + (size_t)(g * MG + r) * DM; f32x4 v[4]; float ss = 0.f;
; #pragma unroll
;         for (int i = 0; i < 4; ++i) { v[i] = *(const f32x4*)(xr + lane * 4 + 256 * i); ss += v[i][0] * v[i][0] + v[i][1] * v[i][1] + v[i][2] * v[i][2] + v[i][3] * v[i][3]; }
;         ss = wave_sum(ss); const float rstd = rsqrtf(ss * (1.f / DM) + EPS);
; #pragma unroll
;         for (int i = 0; i < 4; ++i) { const f32x4 gv = *(const f32x4*)(gw + lane * 4 + 256 * i);
;             u32x2 o = {cvtpk(v[i][0] * rstd * gv[0], v[i][1] * rstd * gv[1]), cvtpk(v[i][2] * rstd * gv[2], v[i][3] * rstd * gv[3])};
;             *(u32x2*)(p.hbuf + (size_t)r * DM + lane * 4 + 256 * i) = o; }
	v_mov_b32_e32 v38, v17
	v_mov_b32_e32 v39, v21
	v_mov_b32_e32 v36, v16
	v_mov_b32_e32 v37, v20
	v_mov_b32_e32 v46, v25
	v_mov_b32_e32 v47, v29
	v_pk_mul_f32 v[38:39], v[38:39], v[38:39]
	v_mov_b32_e32 v40, v18
	v_mov_b32_e32 v41, v22
	v_mov_b32_e32 v44, v24
	v_mov_b32_e32 v45, v28
	v_pk_mul_f32 v[46:47], v[46:47], v[46:47]
	v_pk_fma_f32 v[36:37], v[36:37], v[36:37], v[38:39]
	v_mov_b32_e32 v42, v19
	v_mov_b32_e32 v43, v23
	v_mov_b32_e32 v48, v26
	v_mov_b32_e32 v49, v30
	v_pk_fma_f32 v[38:39], v[44:45], v[44:45], v[46:47]
	v_pk_fma_f32 v[36:37], v[40:41], v[40:41], v[36:37]
	v_mov_b32_e32 v50, v27
	v_mov_b32_e32 v51, v31
	v_pk_fma_f32 v[38:39], v[48:49], v[48:49], v[38:39]
	v_pk_fma_f32 v[36:37], v[42:43], v[42:43], v[36:37]
	v_pk_fma_f32 v[38:39], v[50:51], v[50:51], v[38:39]
	v_add_f32_e32 v0, v36, v37
	v_add_f32_e32 v0, v0, v38
	v_add_f32_e32 v0, v0, v39
	ds_bpermute_b32 v3, v10, v0
	s_waitcnt lgkmcnt(0)
	v_add_f32_e32 v0, v0, v3
	ds_bpermute_b32 v3, v11, v0
	s_waitcnt lgkmcnt(0)
	v_add_f32_e32 v0, v0, v3
	ds_bpermute_b32 v3, v12, v0
	s_waitcnt lgkmcnt(0)
	v_add_f32_e32 v0, v0, v3
	ds_bpermute_b32 v3, v13, v0
	s_waitcnt lgkmcnt(0)
	v_add_f32_e32 v0, v0, v3
	ds_bpermute_b32 v3, v14, v0
	s_waitcnt lgkmcnt(0)
	v_add_f32_e32 v0, v0, v3
	ds_bpermute_b32 v3, v15, v0
	s_waitcnt lgkmcnt(0)
	v_add_f32_e32 v0, v0, v3
	v_fmamk_f32 v0, v0, 0x3a800000, v199
	v_mul_f32_e32 v3, 0x4b800000, v0
	v_cmp_gt_f32_e32 vcc, s85, v0
	s_nop 1
	v_cndmask_b32_e32 v0, v0, v3, vcc
	v_rsq_f32_e32 v0, v0
	s_nop 0
	v_mul_f32_e32 v3, 0x45800000, v0
	v_cndmask_b32_e32 v0, v0, v3, vcc
	v_mul_f32_e32 v40, v16, v0
	v_mul_f32_e32 v41, v17, v0
	v_mul_f32_e32 v42, v18, v0
	v_mul_f32_e32 v43, v19, v0
	v_mul_f32_e32 v40, v32, v40
	v_mul_f32_e32 v41, v33, v41
	v_mul_f32_e32 v42, v34, v42
	v_mul_f32_e32 v43, v35, v43
	v_cvt_pk_bf16_f32 v48, v40, v41
	v_cvt_pk_bf16_f32 v49, v42, v43
	global_store_dwordx2 v[8:9], v[48:49], off offset:-1024
	v_mul_f32_e32 v44, v20, v0
	v_mul_f32_e32 v45, v21, v0
	v_mul_f32_e32 v46, v22, v0
	v_mul_f32_e32 v47, v23, v0
	v_mul_f32_e32 v44, v52, v44
	v_mul_f32_e32 v45, v53, v45
	v_mul_f32_e32 v46, v54, v46
	v_mul_f32_e32 v47, v55, v47
	v_cvt_pk_bf16_f32 v50, v44, v45
	v_cvt_pk_bf16_f32 v51, v46, v47
	global_store_dwordx2 v[8:9], v[50:51], off offset:-512
	v_mul_f32_e32 v40, v24, v0
	v_mul_f32_e32 v41, v25, v0
	v_mul_f32_e32 v42, v26, v0
	v_mul_f32_e32 v43, v27, v0
	v_mul_f32_e32 v40, v56, v40
	v_mul_f32_e32 v41, v57, v41
	v_mul_f32_e32 v42, v58, v42
	v_mul_f32_e32 v43, v59, v43
	v_cvt_pk_bf16_f32 v48, v40, v41
	v_cvt_pk_bf16_f32 v49, v42, v43
	global_store_dwordx2 v[8:9], v[48:49], off
	v_mul_f32_e32 v44, v28, v0
	v_mul_f32_e32 v45, v29, v0
	v_mul_f32_e32 v46, v30, v0
	v_mul_f32_e32 v47, v31, v0
	v_mul_f32_e32 v44, v60, v44
	v_mul_f32_e32 v45, v61, v45
	v_mul_f32_e32 v46, v62, v46
	v_mul_f32_e32 v47, v63, v47
	v_cvt_pk_bf16_f32 v50, v44, v45
	v_cvt_pk_bf16_f32 v51, v46, v47
	global_store_dwordx2 v[8:9], v[50:51], off offset:512
	v_lshl_add_u64 v[8:9], v[8:9], 0, s[24:25]
	s_waitcnt vmcnt(20)
	v_mov_b32_e32 v38, v65
	v_mov_b32_e32 v39, v69
	v_mov_b32_e32 v36, v64
	v_mov_b32_e32 v37, v68
	v_mov_b32_e32 v46, v73
	v_mov_b32_e32 v47, v77
	v_pk_mul_f32 v[38:39], v[38:39], v[38:39]
	v_mov_b32_e32 v40, v66
	v_mov_b32_e32 v41, v70
	v_mov_b32_e32 v44, v72
	v_mov_b32_e32 v45, v76
	v_pk_mul_f32 v[46:47], v[46:47], v[46:47]
	v_pk_fma_f32 v[36:37], v[36:37], v[36:37], v[38:39]
	v_mov_b32_e32 v42, v67
	v_mov_b32_e32 v43, v71
	v_mov_b32_e32 v48, v74
	v_mov_b32_e32 v49, v78
	v_pk_fma_f32 v[38:39], v[44:45], v[44:45], v[46:47]
	v_pk_fma_f32 v[36:37], v[40:41], v[40:41], v[36:37]
	v_mov_b32_e32 v50, v75
	v_mov_b32_e32 v51, v79
	v_pk_fma_f32 v[38:39], v[48:49], v[48:49], v[38:39]
	v_pk_fma_f32 v[36:37], v[42:43], v[42:43], v[36:37]
	v_pk_fma_f32 v[38:39], v[50:51], v[50:51], v[38:39]
	v_add_f32_e32 v0, v36, v37
	v_add_f32_e32 v0, v0, v38
	v_add_f32_e32 v0, v0, v39
	ds_bpermute_b32 v3, v10, v0
	s_waitcnt lgkmcnt(0)
	v_add_f32_e32 v0, v0, v3
	ds_bpermute_b32 v3, v11, v0
	s_waitcnt lgkmcnt(0)
	v_add_f32_e32 v0, v0, v3
	ds_bpermute_b32 v3, v12, v0
	s_waitcnt lgkmcnt(0)
	v_add_f32_e32 v0, v0, v3
	ds_bpermute_b32 v3, v13, v0
	s_waitcnt lgkmcnt(0)
	v_add_f32_e32 v0, v0, v3
	ds_bpermute_b32 v3, v14, v0
	s_waitcnt lgkmcnt(0)
	v_add_f32_e32 v0, v0, v3
	ds_bpermute_b32 v3, v15, v0
	s_waitcnt lgkmcnt(0)
	v_add_f32_e32 v0, v0, v3
	v_fmamk_f32 v0, v0, 0x3a800000, v199
	v_mul_f32_e32 v3, 0x4b800000, v0
	v_cmp_gt_f32_e32 vcc, s85, v0
	s_nop 1
	v_cndmask_b32_e32 v0, v0, v3, vcc
	v_rsq_f32_e32 v0, v0
	s_nop 0
	v_mul_f32_e32 v3, 0x45800000, v0
	v_cndmask_b32_e32 v0, v0, v3, vcc
	v_mul_f32_e32 v40, v64, v0
	v_mul_f32_e32 v41, v65, v0
	v_mul_f32_e32 v42, v66, v0
	v_mul_f32_e32 v43, v67, v0
	v_mul_f32_e32 v40, v32, v40
	v_mul_f32_e32 v41, v33, v41
	v_mul_f32_e32 v42, v34, v42
	v_mul_f32_e32 v43, v35, v43
	v_cvt_pk_bf16_f32 v48, v40, v41
	v_cvt_pk_bf16_f32 v49, v42, v43
	global_store_dwordx2 v[8:9], v[48:49], off offset:-1024
	v_mul_f32_e32 v44, v68, v0
	v_mul_f32_e32 v45, v69, v0
	v_mul_f32_e32 v46, v70, v0
	v_mul_f32_e32 v47, v71, v0
	v_mul_f32_e32 v44, v52, v44
	v_mul_f32_e32 v45, v53, v45
	v_mul_f32_e32 v46, v54, v46
	v_mul_f32_e32 v47, v55, v47
	v_cvt_pk_bf16_f32 v50, v44, v45
	v_cvt_pk_bf16_f32 v51, v46, v47
	global_store_dwordx2 v[8:9], v[50:51], off offset:-512
	v_mul_f32_e32 v40, v72, v0
	v_mul_f32_e32 v41, v73, v0
	v_mul_f32_e32 v42, v74, v0
	v_mul_f32_e32 v43, v75, v0
	v_mul_f32_e32 v40, v56, v40
	v_mul_f32_e32 v41, v57, v41
	v_mul_f32_e32 v42, v58, v42
	v_mul_f32_e32 v43, v59, v43
	v_cvt_pk_bf16_f32 v48, v40, v41
	v_cvt_pk_bf16_f32 v49, v42, v43
	global_store_dwordx2 v[8:9], v[48:49], off
	v_mul_f32_e32 v44, v76, v0
	v_mul_f32_e32 v45, v77, v0
	v_mul_f32_e32 v46, v78, v0
	v_mul_f32_e32 v47, v79, v0
	v_mul_f32_e32 v44, v60, v44
	v_mul_f32_e32 v45, v61, v45
	v_mul_f32_e32 v46, v62, v46
	v_mul_f32_e32 v47, v63, v47
	v_cvt_pk_bf16_f32 v50, v44, v45
	v_cvt_pk_bf16_f32 v51, v46, v47
	global_store_dwordx2 v[8:9], v[50:51], off offset:512
	v_lshl_add_u64 v[8:9], v[8:9], 0, s[24:25]
	s_waitcnt vmcnt(16)
; __device__ __forceinline__ unsigned cvtpk(float lo, float hi) { unsigned r; asm volatile("v_cvt_pk_bf16_f32 %0, %1, %2" : "=v"(r) : "v"(lo), "v"(hi)); return r; }
; __device__ __forceinline__ float wave_sum(float v) { for (int o = 32; o >= 1; o >>= 1) v += __shfl_xor(v, o); return v; }
; __device__ __forceinline__ void step_norm(const Params& p, int l, int g) {
;     ...
;     for (int r = gwv; r < MG; r += nwv) {
;         const float* xr = src + (size_t)(g * MG + r) * DM; f32x4 v[4]; float ss = 0.f;
; #pragma unroll
;         for (int i = 0; i < 4; ++i) { v[i] = *(const f32x4*)(xr + lane * 4 + 256 * i); ss += v[i][0] * v[i][0] + v[i][1] * v[i][1] + v[i][2] * v[i][2] + v[i][3] * v[i][3]; }
;         ss = wave_sum(ss); const float rstd = rsqrtf(ss * (1.f / DM) + EPS);
; #pragma unroll
;         for (int i = 0; i < 4; ++i) { const f32x4 gv = *(const f32x4*)(gw + lane * 4 + 256 * i);
;             u32x2 o = {cvtpk(v[i][0] * rstd * gv[0], v[i][1] * rstd * gv[1]), cvtpk(v[i][2] * rstd * gv[2], v[i][3] * rstd * gv[3])};
;             *(u32x2*)(p.hbuf + (size_t)r * DM + lane * 4 + 256 * i) = o; }
	v_mov_b32_e32 v38, v81
	v_mov_b32_e32 v39, v85
	v_mov_b32_e32 v36, v80
	v_mov_b32_e32 v37, v84
	v_mov_b32_e32 v46, v89
	v_mov_b32_e32 v47, v93
	v_pk_mul_f32 v[38:39], v[38:39], v[38:39]
	v_mov_b32_e32 v40, v82
	v_mov_b32_e32 v41, v86
	v_mov_b32_e32 v44, v88
	v_mov_b32_e32 v45, v92
	v_pk_mul_f32 v[46:47], v[46:47], v[46:47]
	v_pk_fma_f32 v[36:37], v[36:37], v[36:37], v[38:39]
	v_mov_b32_e32 v42, v83
	v_mov_b32_e32 v43, v87
	v_mov_b32_e32 v48, v90
	v_mov_b32_e32 v49, v94
	v_pk_fma_f32 v[38:39], v[44:45], v[44:45], v[46:47]
	v_pk_fma_f32 v[36:37], v[40:41], v[40:41], v[36:37]
	v_mov_b32_e32 v50, v91
	v_mov_b32_e32 v51, v95
	v_pk_fma_f32 v[38:39], v[48:49], v[48:49], v[38:39]
	v_pk_fma_f32 v[36:37], v[42:43], v[42:43], v[36:37]
	v_pk_fma_f32 v[38:39], v[50:51], v[50:51], v[38:39]
	v_add_f32_e32 v0, v36, v37
	v_add_f32_e32 v0, v0, v38
	v_add_f32_e32 v0, v0, v39
	ds_bpermute_b32 v3, v10, v0
	s_waitcnt lgkmcnt(0)
	v_add_f32_e32 v0, v0, v3
	ds_bpermute_b32 v3, v11, v0
	s_waitcnt lgkmcnt(0)
	v_add_f32_e32 v0, v0, v3
	ds_bpermute_b32 v3, v12, v0
	s_waitcnt lgkmcnt(0)
	v_add_f32_e32 v0, v0, v3
	ds_bpermute_b32 v3, v13, v0
	s_waitcnt lgkmcnt(0)
	v_add_f32_e32 v0, v0, v3
	ds_bpermute_b32 v3, v14, v0
	s_waitcnt lgkmcnt(0)
	v_add_f32_e32 v0, v0, v3
	ds_bpermute_b32 v3, v15, v0
	s_waitcnt lgkmcnt(0)
	v_add_f32_e32 v0, v0, v3
	v_fmamk_f32 v0, v0, 0x3a800000, v199
	v_mul_f32_e32 v3, 0x4b800000, v0
	v_cmp_gt_f32_e32 vcc, s85, v0
	s_nop 1
	v_cndmask_b32_e32 v0, v0, v3, vcc
	v_rsq_f32_e32 v0, v0
	s_nop 0
	v_mul_f32_e32 v3, 0x45800000, v0
	v_cndmask_b32_e32 v0, v0, v3, vcc
	v_mul_f32_e32 v40, v80, v0
	v_mul_f32_e32 v41, v81, v0
	v_mul_f32_e32 v42, v82, v0
	v_mul_f32_e32 v43, v83, v0
	v_mul_f32_e32 v40, v32, v40
	v_mul_f32_e32 v41, v33, v41
	v_mul_f32_e32 v42, v34, v42
	v_mul_f32_e32 v43, v35, v43
	v_cvt_pk_bf16_f32 v48, v40, v41
	v_cvt_pk_bf16_f32 v49, v42, v43
	global_store_dwordx2 v[8:9], v[48:49], off offset:-1024
	v_mul_f32_e32 v44, v84, v0
	v_mul_f32_e32 v45, v85, v0
	v_mul_f32_e32 v46, v86, v0
	v_mul_f32_e32 v47, v87, v0
	v_mul_f32_e32 v44, v52, v44
	v_mul_f32_e32 v45, v53, v45
	v_mul_f32_e32 v46, v54, v46
	v_mul_f32_e32 v47, v55, v47
	v_cvt_pk_bf16_f32 v50, v44, v45
	v_cvt_pk_bf16_f32 v51, v46, v47
	global_store_dwordx2 v[8:9], v[50:51], off offset:-512
	v_mul_f32_e32 v40, v88, v0
	v_mul_f32_e32 v41, v89, v0
	v_mul_f32_e32 v42, v90, v0
	v_mul_f32_e32 v43, v91, v0
	v_mul_f32_e32 v40, v56, v40
	v_mul_f32_e32 v41, v57, v41
	v_mul_f32_e32 v42, v58, v42
	v_mul_f32_e32 v43, v59, v43
	v_cvt_pk_bf16_f32 v48, v40, v41
	v_cvt_pk_bf16_f32 v49, v42, v43
	global_store_dwordx2 v[8:9], v[48:49], off
	v_mul_f32_e32 v44, v92, v0
	v_mul_f32_e32 v45, v93, v0
	v_mul_f32_e32 v46, v94, v0
	v_mul_f32_e32 v47, v95, v0
	v_mul_f32_e32 v44, v60, v44
	v_mul_f32_e32 v45, v61, v45
	v_mul_f32_e32 v46, v62, v46
	v_mul_f32_e32 v47, v63, v47
	v_cvt_pk_bf16_f32 v50, v44, v45
	v_cvt_pk_bf16_f32 v51, v46, v47
	global_store_dwordx2 v[8:9], v[50:51], off offset:512
	v_lshl_add_u64 v[8:9], v[8:9], 0, s[24:25]
	s_waitcnt vmcnt(12)
	v_mov_b32_e32 v38, v97
	v_mov_b32_e32 v39, v101
	v_mov_b32_e32 v36, v96
	v_mov_b32_e32 v37, v100
	v_mov_b32_e32 v46, v105
	v_mov_b32_e32 v47, v109
	v_pk_mul_f32 v[38:39], v[38:39], v[38:39]
	v_mov_b32_e32 v40, v98
	v_mov_b32_e32 v41, v102
	v_mov_b32_e32 v44, v104
	v_mov_b32_e32 v45, v108
	v_pk_mul_f32 v[46:47], v[46:47], v[46:47]
	v_pk_fma_f32 v[36:37], v[36:37], v[36:37], v[38:39]
	v_mov_b32_e32 v42, v99
	v_mov_b32_e32 v43, v103
	v_mov_b32_e32 v48, v106
	v_mov_b32_e32 v49, v110
	v_pk_fma_f32 v[38:39], v[44:45], v[44:45], v[46:47]
	v_pk_fma_f32 v[36:37], v[40:41], v[40:41], v[36:37]
	v_mov_b32_e32 v50, v107
	v_mov_b32_e32 v51, v111
	v_pk_fma_f32 v[38:39], v[48:49], v[48:49], v[38:39]
	v_pk_fma_f32 v[36:37], v[42:43], v[42:43], v[36:37]
	v_pk_fma_f32 v[38:39], v[50:51], v[50:51], v[38:39]
	v_add_f32_e32 v0, v36, v37
	v_add_f32_e32 v0, v0, v38
	v_add_f32_e32 v0, v0, v39
	ds_bpermute_b32 v3, v10, v0
	s_waitcnt lgkmcnt(0)
	v_add_f32_e32 v0, v0, v3
	ds_bpermute_b32 v3, v11, v0
	s_waitcnt lgkmcnt(0)
	v_add_f32_e32 v0, v0, v3
	ds_bpermute_b32 v3, v12, v0
	s_waitcnt lgkmcnt(0)
	v_add_f32_e32 v0, v0, v3
	ds_bpermute_b32 v3, v13, v0
	s_waitcnt lgkmcnt(0)
	v_add_f32_e32 v0, v0, v3
	ds_bpermute_b32 v3, v14, v0
	s_waitcnt lgkmcnt(0)
	v_add_f32_e32 v0, v0, v3
	ds_bpermute_b32 v3, v15, v0
	s_waitcnt lgkmcnt(0)
	v_add_f32_e32 v0, v0, v3
	v_fmamk_f32 v0, v0, 0x3a800000, v199
	v_mul_f32_e32 v3, 0x4b800000, v0
	v_cmp_gt_f32_e32 vcc, s85, v0
	s_nop 1
	v_cndmask_b32_e32 v0, v0, v3, vcc
	v_rsq_f32_e32 v0, v0
	s_nop 0
	v_mul_f32_e32 v3, 0x45800000, v0
	v_cndmask_b32_e32 v0, v0, v3, vcc
	v_mul_f32_e32 v40, v96, v0
	v_mul_f32_e32 v41, v97, v0
	v_mul_f32_e32 v42, v98, v0
	v_mul_f32_e32 v43, v99, v0
	v_mul_f32_e32 v40, v32, v40
	v_mul_f32_e32 v41, v33, v41
	v_mul_f32_e32 v42, v34, v42
	v_mul_f32_e32 v43, v35, v43
	v_cvt_pk_bf16_f32 v48, v40, v41
	v_cvt_pk_bf16_f32 v49, v42, v43
	global_store_dwordx2 v[8:9], v[48:49], off offset:-1024
	v_mul_f32_e32 v44, v100, v0
	v_mul_f32_e32 v45, v101, v0
	v_mul_f32_e32 v46, v102, v0
	v_mul_f32_e32 v47, v103, v0
	v_mul_f32_e32 v44, v52, v44
	v_mul_f32_e32 v45, v53, v45
	v_mul_f32_e32 v46, v54, v46
	v_mul_f32_e32 v47, v55, v47
	v_cvt_pk_bf16_f32 v50, v44, v45
	v_cvt_pk_bf16_f32 v51, v46, v47
	global_store_dwordx2 v[8:9], v[50:51], off offset:-512
	v_mul_f32_e32 v40, v104, v0
	v_mul_f32_e32 v41, v105, v0
	v_mul_f32_e32 v42, v106, v0
	v_mul_f32_e32 v43, v107, v0
	v_mul_f32_e32 v40, v56, v40
	v_mul_f32_e32 v41, v57, v41
	v_mul_f32_e32 v42, v58, v42
	v_mul_f32_e32 v43, v59, v43
	v_cvt_pk_bf16_f32 v48, v40, v41
	v_cvt_pk_bf16_f32 v49, v42, v43
	global_store_dwordx2 v[8:9], v[48:49], off
	v_mul_f32_e32 v44, v108, v0
	v_mul_f32_e32 v45, v109, v0
	v_mul_f32_e32 v46, v110, v0
	v_mul_f32_e32 v47, v111, v0
	v_mul_f32_e32 v44, v60, v44
	v_mul_f32_e32 v45, v61, v45
	v_mul_f32_e32 v46, v62, v46
	v_mul_f32_e32 v47, v63, v47
	v_cvt_pk_bf16_f32 v50, v44, v45
	v_cvt_pk_bf16_f32 v51, v46, v47
	global_store_dwordx2 v[8:9], v[50:51], off offset:512
	v_lshl_add_u64 v[8:9], v[8:9], 0, s[24:25]
